# attention hot path: redundant v_max x,x canonicalisations folded away (6 VALU per key tile), on top of the mega bundle
# baseline (speedup 1.0000x reference)
.LBB0_1046:
	s_or_b64 exec, exec, s[22:23]
	global_load_dwordx4 v[152:155], v[168:169], off
	s_and_b32 s25, s4, 1
	v_cmp_le_i32_e32 vcc, s4, v185
	s_and_saveexec_b64 s[22:23], vcc
	s_cbranch_execz .LBB0_1052
	s_mul_i32 s26, s25, 0x5600
	s_add_i32 s26, s26, 0
	v_add3_u32 v187, s26, v184, v166
	ds_read_b128 v[64:67], v187
	ds_read_b128 v[188:191], v187 offset:32
	s_waitcnt lgkmcnt(1)
	v_mfma_f32_32x32x16_bf16 v[80:95], v[64:67], v[132:135], 0
	v_mfma_f32_32x32x16_bf16 v[64:79], v[64:67], v[140:143], 0
	s_waitcnt lgkmcnt(0)
	v_mfma_f32_32x32x16_bf16 v[80:95], v[188:191], v[124:127], v[80:95]
	v_mfma_f32_32x32x16_bf16 v[64:79], v[188:191], v[136:139], v[64:79]
	ds_read_b128 v[188:191], v187 offset:64
	ds_read_b128 v[192:195], v187 offset:96
	s_waitcnt lgkmcnt(1)
	v_mfma_f32_32x32x16_bf16 v[80:95], v[188:191], v[120:123], v[80:95]
	s_waitcnt lgkmcnt(0)
	v_mfma_f32_32x32x16_bf16 v[80:95], v[192:195], v[116:119], v[80:95]
	v_mfma_f32_32x32x16_bf16 v[64:79], v[188:191], v[128:131], v[64:79]
	ds_read_b128 v[188:191], v187 offset:128
	ds_read_b128 v[196:199], v187 offset:160
	s_nop 1
	s_waitcnt lgkmcnt(1)
	v_mfma_f32_32x32x16_bf16 v[80:95], v[188:191], v[112:115], v[80:95]
	s_waitcnt lgkmcnt(0)
	v_mfma_f32_32x32x16_bf16 v[80:95], v[196:199], v[108:111], v[80:95]
	v_mfma_f32_32x32x16_bf16 v[64:79], v[192:195], v[104:107], v[64:79]
	s_nop 10
	v_max_f32_e32 v192, v80, v81
	v_max3_f32 v192, v192, v82, v83
	v_max3_f32 v192, v192, v84, v85
	v_max3_f32 v192, v192, v86, v87
	v_max3_f32 v192, v192, v88, v89
	v_mfma_f32_32x32x16_bf16 v[64:79], v[188:191], v[100:103], v[64:79]
	v_max3_f32 v192, v192, v90, v91
	v_max3_f32 v188, v192, v92, v93
	v_max3_f32 v188, v188, v94, v95
	v_mov_b32_e32 v189, v188
	s_nop 1
	v_permlane32_swap_b32_e32 v189, v188
	s_waitcnt lgkmcnt(0)
	v_mfma_f32_32x32x16_bf16 v[64:79], v[196:199], v[96:99], v[64:79]
	v_max_f32_e32 v188, v188, v189
	v_add_f32_e32 v189, 0x41000000, v161
	v_cmp_gt_f32_e32 vcc, v188, v189
	s_cbranch_vccz .LBB0_1049
	v_max_f32_e32 v188, v188, v188
	v_max_f32_e32 v189, v161, v161
	v_max_f32_e32 v189, v189, v188
	v_sub_f32_e32 v161, v161, v189
	v_exp_f32_e32 v188, v161
	v_mov_b32_e32 v161, v189
	v_mul_f32_e32 v162, v162, v188
	v_pk_mul_f32 v[62:63], v[62:63], v[188:189] op_sel_hi:[1,0]
	v_pk_mul_f32 v[60:61], v[60:61], v[188:189] op_sel_hi:[1,0]
	v_pk_mul_f32 v[58:59], v[58:59], v[188:189] op_sel_hi:[1,0]
	v_pk_mul_f32 v[56:57], v[56:57], v[188:189] op_sel_hi:[1,0]
	v_pk_mul_f32 v[54:55], v[54:55], v[188:189] op_sel_hi:[1,0]
	v_pk_mul_f32 v[52:53], v[52:53], v[188:189] op_sel_hi:[1,0]
	v_pk_mul_f32 v[50:51], v[50:51], v[188:189] op_sel_hi:[1,0]
	v_pk_mul_f32 v[48:49], v[48:49], v[188:189] op_sel_hi:[1,0]
	v_pk_mul_f32 v[46:47], v[46:47], v[188:189] op_sel_hi:[1,0]
	v_pk_mul_f32 v[44:45], v[44:45], v[188:189] op_sel_hi:[1,0]
	v_pk_mul_f32 v[42:43], v[42:43], v[188:189] op_sel_hi:[1,0]
	v_pk_mul_f32 v[40:41], v[40:41], v[188:189] op_sel_hi:[1,0]
	v_pk_mul_f32 v[38:39], v[38:39], v[188:189] op_sel_hi:[1,0]
	v_pk_mul_f32 v[36:37], v[36:37], v[188:189] op_sel_hi:[1,0]
	v_pk_mul_f32 v[34:35], v[34:35], v[188:189] op_sel_hi:[1,0]
	v_pk_mul_f32 v[32:33], v[32:33], v[188:189] op_sel_hi:[1,0]
.LBB0_1049:
	v_pk_add_f32 v[224:225], v[80:81], v[160:161] op_sel:[0,1] op_sel_hi:[1,1] neg_lo:[0,1] neg_hi:[0,1]
	v_pk_add_f32 v[226:227], v[82:83], v[160:161] op_sel:[0,1] op_sel_hi:[1,1] neg_lo:[0,1] neg_hi:[0,1]
	v_pk_add_f32 v[228:229], v[84:85], v[160:161] op_sel:[0,1] op_sel_hi:[1,1] neg_lo:[0,1] neg_hi:[0,1]
	v_pk_add_f32 v[230:231], v[86:87], v[160:161] op_sel:[0,1] op_sel_hi:[1,1] neg_lo:[0,1] neg_hi:[0,1]
	v_pk_add_f32 v[232:233], v[88:89], v[160:161] op_sel:[0,1] op_sel_hi:[1,1] neg_lo:[0,1] neg_hi:[0,1]
	v_pk_add_f32 v[234:235], v[90:91], v[160:161] op_sel:[0,1] op_sel_hi:[1,1] neg_lo:[0,1] neg_hi:[0,1]
	v_pk_add_f32 v[236:237], v[92:93], v[160:161] op_sel:[0,1] op_sel_hi:[1,1] neg_lo:[0,1] neg_hi:[0,1]
	v_pk_add_f32 v[238:239], v[94:95], v[160:161] op_sel:[0,1] op_sel_hi:[1,1] neg_lo:[0,1] neg_hi:[0,1]
	v_exp_f32_e32 v90, v226
	v_exp_f32_e32 v91, v227
	v_exp_f32_e32 v94, v230
	v_exp_f32_e32 v95, v231
	v_exp_f32_e32 v82, v234
	v_exp_f32_e32 v86, v238
	v_exp_f32_e32 v87, v239
	v_exp_f32_e32 v83, v235
	v_exp_f32_e32 v88, v224
	v_exp_f32_e32 v89, v225
	v_exp_f32_e32 v80, v232
	v_exp_f32_e32 v81, v233
	v_pk_add_f32 v[192:193], v[94:95], v[86:87]
	v_pk_add_f32 v[194:195], v[90:91], v[82:83]
	v_pk_add_f32 v[192:193], v[194:195], v[192:193]
	v_max_f32_e32 v194, v64, v65
	v_max3_f32 v194, v194, v66, v67
	v_max3_f32 v194, v194, v68, v69
	v_exp_f32_e32 v92, v228
	v_exp_f32_e32 v93, v229
	v_exp_f32_e32 v84, v236
	v_exp_f32_e32 v85, v237
	v_max3_f32 v194, v194, v70, v71
	v_max3_f32 v194, v194, v72, v73
	v_max3_f32 v194, v194, v74, v75
	v_max3_f32 v194, v194, v76, v77
	v_pk_add_f32 v[188:189], v[92:93], v[84:85]
	v_pk_add_f32 v[190:191], v[88:89], v[80:81]
	v_max3_f32 v194, v194, v78, v79
	v_mov_b32_e32 v195, v194
	s_nop 1
	v_permlane32_swap_b32_e32 v195, v194
	v_pk_add_f32 v[188:189], v[190:191], v[188:189]
	v_add_f32_e32 v191, 0x41000000, v167
	v_pk_add_f32 v[188:189], v[188:189], v[192:193]
	s_waitcnt lgkmcnt(0)
	v_add_f32_e32 v188, v188, v189
	v_mov_b32_e32 v189, v188
	s_nop 1
	v_permlane32_swap_b32_e32 v189, v188
	v_max_f32_e32 v190, v194, v195
	v_cmp_gt_f32_e32 vcc, v190, v191
	s_cbranch_vccz .LBB0_1051
	v_max_f32_e32 v190, v190, v190
	v_max_f32_e32 v191, v167, v167
	v_max_f32_e32 v191, v191, v190
	v_sub_f32_e32 v167, v167, v191
	v_exp_f32_e32 v190, v167
	v_mov_b32_e32 v167, v191
	v_mul_f32_e32 v160, v160, v190
	v_pk_mul_f32 v[30:31], v[30:31], v[190:191] op_sel_hi:[1,0]
	v_pk_mul_f32 v[28:29], v[28:29], v[190:191] op_sel_hi:[1,0]
	v_pk_mul_f32 v[26:27], v[26:27], v[190:191] op_sel_hi:[1,0]
	v_pk_mul_f32 v[24:25], v[24:25], v[190:191] op_sel_hi:[1,0]
	v_pk_mul_f32 v[22:23], v[22:23], v[190:191] op_sel_hi:[1,0]
	v_pk_mul_f32 v[20:21], v[20:21], v[190:191] op_sel_hi:[1,0]
	v_pk_mul_f32 v[18:19], v[18:19], v[190:191] op_sel_hi:[1,0]
	v_pk_mul_f32 v[16:17], v[16:17], v[190:191] op_sel_hi:[1,0]
	v_pk_mul_f32 v[14:15], v[14:15], v[190:191] op_sel_hi:[1,0]
	v_pk_mul_f32 v[12:13], v[12:13], v[190:191] op_sel_hi:[1,0]
	v_pk_mul_f32 v[10:11], v[10:11], v[190:191] op_sel_hi:[1,0]
	v_pk_mul_f32 v[8:9], v[8:9], v[190:191] op_sel_hi:[1,0]
	v_pk_mul_f32 v[6:7], v[6:7], v[190:191] op_sel_hi:[1,0]
	v_pk_mul_f32 v[4:5], v[4:5], v[190:191] op_sel_hi:[1,0]
	v_pk_mul_f32 v[2:3], v[2:3], v[190:191] op_sel_hi:[1,0]
	v_pk_mul_f32 v[0:1], v[0:1], v[190:191] op_sel_hi:[1,0]
